# GEMM main loop: per-MFMA-cluster s_setprio flips removed (priority-flip A/B on the 8-phase template)
# speedup vs baseline: 1.0083x; 1.0083x over previous
.LBB0_66:
	v_add_u32_e32 v0, s61, v242
	s_waitcnt lgkmcnt(0)
	ds_read_b128 v[130:133], v0
	ds_read_b128 v[134:137], v0 offset:1024
	ds_read_b128 v[138:141], v0 offset:2048
	ds_read_b128 v[142:145], v0 offset:3072
	v_add_u32_e32 v0, s20, v242
	ds_read_b128 v[146:149], v0
	ds_read_b128 v[150:153], v0 offset:1024
	ds_read_b128 v[154:157], v0 offset:2048
	ds_read_b128 v[158:161], v0 offset:3072
	s_add_i32 s14, s10, 2
	s_add_u32 s15, s0, 0x80
	s_addc_u32 s11, s1, 0
	s_cmp_eq_u32 s27, s10
	s_cselect_b32 s10, s22, s15
	s_cselect_b32 s11, s23, s11
	s_cselect_b32 s53, s25, s13
	s_cselect_b32 s52, s24, s12
	v_lshl_add_u64 v[216:217], s[0:1], 0, v[194:195]
	s_add_i32 m0, s5, 0xc000
	ds_read_b128 v[162:165], v246
	ds_read_b128 v[166:169], v246 offset:1024
	ds_read_b128 v[170:173], v246 offset:2048
	ds_read_b128 v[174:177], v246 offset:3072
	ds_read_b128 v[200:203], v246 offset:4096
	ds_read_b128 v[204:207], v246 offset:5120
	ds_read_b128 v[208:211], v246 offset:6144
	ds_read_b128 v[212:215], v246 offset:7168
	global_load_lds_dwordx4 v[216:217], off
	v_lshl_add_u64 v[216:217], s[0:1], 0, v[196:197]
	s_add_i32 m0, s5, 0xe000
	s_nop 0
	global_load_lds_dwordx4 v[216:217], off
	s_waitcnt vmcnt(8)
	s_waitcnt lgkmcnt(0)
	s_barrier
	s_waitcnt lgkmcnt(0)
	v_mfma_f32_16x16x32_bf16 v[30:33], v[130:133], v[162:165], v[30:33]
	v_mfma_f32_16x16x32_bf16 v[26:29], v[138:141], v[162:165], v[26:29]
	v_mfma_f32_16x16x32_bf16 v[18:21], v[130:133], v[170:173], v[18:21]
	v_mfma_f32_16x16x32_bf16 v[10:13], v[138:141], v[170:173], v[10:13]
	v_mfma_f32_16x16x32_bf16 v[126:129], v[130:133], v[200:203], v[126:129]
	v_mfma_f32_16x16x32_bf16 v[122:125], v[138:141], v[200:203], v[122:125]
	v_mfma_f32_16x16x32_bf16 v[110:113], v[130:133], v[208:211], v[110:113]
	v_mfma_f32_16x16x32_bf16 v[106:109], v[138:141], v[208:211], v[106:109]
	v_mfma_f32_16x16x32_bf16 v[30:33], v[134:137], v[166:169], v[30:33]
	v_mfma_f32_16x16x32_bf16 v[26:29], v[142:145], v[166:169], v[26:29]
	v_mfma_f32_16x16x32_bf16 v[18:21], v[134:137], v[174:177], v[18:21]
	v_mfma_f32_16x16x32_bf16 v[10:13], v[142:145], v[174:177], v[10:13]
	v_mfma_f32_16x16x32_bf16 v[126:129], v[134:137], v[204:207], v[126:129]
	v_mfma_f32_16x16x32_bf16 v[122:125], v[142:145], v[204:207], v[122:125]
	v_mfma_f32_16x16x32_bf16 v[110:113], v[134:137], v[212:215], v[110:113]
	v_mfma_f32_16x16x32_bf16 v[106:109], v[142:145], v[212:215], v[106:109]
	v_mfma_f32_16x16x32_bf16 v[22:25], v[146:149], v[162:165], v[22:25]
	v_mfma_f32_16x16x32_bf16 v[14:17], v[154:157], v[162:165], v[14:17]
	v_mfma_f32_16x16x32_bf16 v[6:9], v[146:149], v[170:173], v[6:9]
	v_mfma_f32_16x16x32_bf16 v[2:5], v[154:157], v[170:173], v[2:5]
	v_mfma_f32_16x16x32_bf16 v[118:121], v[146:149], v[200:203], v[118:121]
	v_mfma_f32_16x16x32_bf16 v[114:117], v[154:157], v[200:203], v[114:117]
	v_mfma_f32_16x16x32_bf16 v[102:105], v[146:149], v[208:211], v[102:105]
	v_mfma_f32_16x16x32_bf16 v[98:101], v[154:157], v[208:211], v[98:101]
	v_mfma_f32_16x16x32_bf16 v[22:25], v[150:153], v[166:169], v[22:25]
	v_mfma_f32_16x16x32_bf16 v[14:17], v[158:161], v[166:169], v[14:17]
	v_mfma_f32_16x16x32_bf16 v[6:9], v[150:153], v[174:177], v[6:9]
	v_mfma_f32_16x16x32_bf16 v[2:5], v[158:161], v[174:177], v[2:5]
	v_mfma_f32_16x16x32_bf16 v[118:121], v[150:153], v[204:207], v[118:121]
	v_mfma_f32_16x16x32_bf16 v[114:117], v[158:161], v[204:207], v[114:117]
	v_mfma_f32_16x16x32_bf16 v[102:105], v[150:153], v[212:215], v[102:105]
	v_mfma_f32_16x16x32_bf16 v[98:101], v[158:161], v[212:215], v[98:101]
	s_barrier
	s_mov_b32 m0, s62
	v_lshl_add_u64 v[216:217], s[52:53], 0, v[178:179]
	v_lshl_add_u64 v[218:219], s[52:53], 0, v[180:181]
	s_add_u32 s52, s52, s96
	ds_read_b128 v[162:165], v246 offset:16384
	ds_read_b128 v[166:169], v246 offset:17408
	ds_read_b128 v[170:173], v246 offset:18432
	ds_read_b128 v[174:177], v246 offset:19456
	ds_read_b128 v[200:203], v246 offset:20480
	ds_read_b128 v[204:207], v246 offset:21504
	ds_read_b128 v[208:211], v246 offset:22528
	ds_read_b128 v[212:215], v246 offset:23552
	global_load_lds_dwordx4 v[216:217], off
	s_mov_b32 m0, s63
	s_addc_u32 s53, s53, 0
	global_load_lds_dwordx4 v[218:219], off
	v_lshl_add_u64 v[220:221], s[52:53], 0, v[178:179]
	s_mov_b32 m0, s21
	v_lshl_add_u64 v[222:223], s[52:53], 0, v[180:181]
	global_load_lds_dwordx4 v[220:221], off
	s_mov_b32 m0, s4
	v_lshl_add_u64 v[224:225], s[10:11], 0, v[178:179]
	global_load_lds_dwordx4 v[222:223], off
	s_mov_b32 m0, s5
	v_lshl_add_u64 v[226:227], s[10:11], 0, v[180:181]
	global_load_lds_dwordx4 v[224:225], off
	s_mov_b32 m0, s60
	s_nop 0
	global_load_lds_dwordx4 v[226:227], off
	s_waitcnt vmcnt(8)
	s_waitcnt lgkmcnt(0)
	s_barrier
	s_waitcnt lgkmcnt(0)
	v_mfma_f32_16x16x32_bf16 v[94:97], v[130:133], v[162:165], v[94:97]
	v_mfma_f32_16x16x32_bf16 v[90:93], v[138:141], v[162:165], v[90:93]
	v_mfma_f32_16x16x32_bf16 v[78:81], v[130:133], v[170:173], v[78:81]
	v_mfma_f32_16x16x32_bf16 v[74:77], v[138:141], v[170:173], v[74:77]
	v_mfma_f32_16x16x32_bf16 v[62:65], v[130:133], v[200:203], v[62:65]
	v_mfma_f32_16x16x32_bf16 v[58:61], v[138:141], v[200:203], v[58:61]
	v_mfma_f32_16x16x32_bf16 v[46:49], v[130:133], v[208:211], v[46:49]
	v_mfma_f32_16x16x32_bf16 v[42:45], v[138:141], v[208:211], v[42:45]
	v_mfma_f32_16x16x32_bf16 v[94:97], v[134:137], v[166:169], v[94:97]
	v_mfma_f32_16x16x32_bf16 v[90:93], v[142:145], v[166:169], v[90:93]
	v_mfma_f32_16x16x32_bf16 v[78:81], v[134:137], v[174:177], v[78:81]
	v_mfma_f32_16x16x32_bf16 v[74:77], v[142:145], v[174:177], v[74:77]
	v_mfma_f32_16x16x32_bf16 v[62:65], v[134:137], v[204:207], v[62:65]
	v_mfma_f32_16x16x32_bf16 v[58:61], v[142:145], v[204:207], v[58:61]
	v_mfma_f32_16x16x32_bf16 v[46:49], v[134:137], v[212:215], v[46:49]
	v_mfma_f32_16x16x32_bf16 v[42:45], v[142:145], v[212:215], v[42:45]
	v_mfma_f32_16x16x32_bf16 v[86:89], v[146:149], v[162:165], v[86:89]
	v_mfma_f32_16x16x32_bf16 v[82:85], v[154:157], v[162:165], v[82:85]
	v_mfma_f32_16x16x32_bf16 v[70:73], v[146:149], v[170:173], v[70:73]
	v_mfma_f32_16x16x32_bf16 v[66:69], v[154:157], v[170:173], v[66:69]
	v_mfma_f32_16x16x32_bf16 v[54:57], v[146:149], v[200:203], v[54:57]
	v_mfma_f32_16x16x32_bf16 v[50:53], v[154:157], v[200:203], v[50:53]
	v_mfma_f32_16x16x32_bf16 v[38:41], v[146:149], v[208:211], v[38:41]
	v_mfma_f32_16x16x32_bf16 v[34:37], v[154:157], v[208:211], v[34:37]
	v_mfma_f32_16x16x32_bf16 v[86:89], v[150:153], v[166:169], v[86:89]
	v_mfma_f32_16x16x32_bf16 v[82:85], v[158:161], v[166:169], v[82:85]
	v_mfma_f32_16x16x32_bf16 v[70:73], v[150:153], v[174:177], v[70:73]
	v_mfma_f32_16x16x32_bf16 v[66:69], v[158:161], v[174:177], v[66:69]
	v_mfma_f32_16x16x32_bf16 v[54:57], v[150:153], v[204:207], v[54:57]
	v_mfma_f32_16x16x32_bf16 v[50:53], v[158:161], v[204:207], v[50:53]
	v_mfma_f32_16x16x32_bf16 v[38:41], v[150:153], v[212:215], v[38:41]
	v_mfma_f32_16x16x32_bf16 v[34:37], v[158:161], v[212:215], v[34:37]
	s_barrier
	v_add_u32_e32 v0, s6, v242
	ds_read_b128 v[130:133], v0
	ds_read_b128 v[134:137], v0 offset:1024
	ds_read_b128 v[138:141], v0 offset:2048
	ds_read_b128 v[142:145], v0 offset:3072
	v_add_u32_e32 v0, s94, v242
	ds_read_b128 v[146:149], v0
	ds_read_b128 v[150:153], v0 offset:1024
	ds_read_b128 v[154:157], v0 offset:2048
	ds_read_b128 v[158:161], v0 offset:3072
	s_add_u32 s10, s10, s96
	s_addc_u32 s11, s11, 0
	s_mov_b32 m0, s84
	v_lshl_add_u64 v[228:229], s[10:11], 0, v[178:179]
	ds_read_b128 v[162:165], v246 offset:32768
	ds_read_b128 v[166:169], v246 offset:33792
	ds_read_b128 v[170:173], v246 offset:34816
	ds_read_b128 v[174:177], v246 offset:35840
	ds_read_b128 v[200:203], v246 offset:36864
	ds_read_b128 v[204:207], v246 offset:37888
	ds_read_b128 v[208:211], v246 offset:38912
	ds_read_b128 v[212:215], v246 offset:39936
	global_load_lds_dwordx4 v[228:229], off
	v_lshl_add_u64 v[228:229], s[10:11], 0, v[180:181]
	s_mov_b32 m0, s26
	s_nop 0
	global_load_lds_dwordx4 v[228:229], off
	s_waitcnt vmcnt(8)
	s_waitcnt lgkmcnt(0)
	s_barrier
	s_waitcnt lgkmcnt(0)
	v_mfma_f32_16x16x32_bf16 v[30:33], v[130:133], v[162:165], v[30:33]
	v_mfma_f32_16x16x32_bf16 v[26:29], v[138:141], v[162:165], v[26:29]
	v_mfma_f32_16x16x32_bf16 v[18:21], v[130:133], v[170:173], v[18:21]
	v_mfma_f32_16x16x32_bf16 v[10:13], v[138:141], v[170:173], v[10:13]
	v_mfma_f32_16x16x32_bf16 v[126:129], v[130:133], v[200:203], v[126:129]
	v_mfma_f32_16x16x32_bf16 v[122:125], v[138:141], v[200:203], v[122:125]
	v_mfma_f32_16x16x32_bf16 v[110:113], v[130:133], v[208:211], v[110:113]
	v_mfma_f32_16x16x32_bf16 v[106:109], v[138:141], v[208:211], v[106:109]
	v_mfma_f32_16x16x32_bf16 v[30:33], v[134:137], v[166:169], v[30:33]
	v_mfma_f32_16x16x32_bf16 v[26:29], v[142:145], v[166:169], v[26:29]
	v_mfma_f32_16x16x32_bf16 v[18:21], v[134:137], v[174:177], v[18:21]
	v_mfma_f32_16x16x32_bf16 v[10:13], v[142:145], v[174:177], v[10:13]
	v_mfma_f32_16x16x32_bf16 v[126:129], v[134:137], v[204:207], v[126:129]
	v_mfma_f32_16x16x32_bf16 v[122:125], v[142:145], v[204:207], v[122:125]
	v_mfma_f32_16x16x32_bf16 v[110:113], v[134:137], v[212:215], v[110:113]
	v_mfma_f32_16x16x32_bf16 v[106:109], v[142:145], v[212:215], v[106:109]
	v_mfma_f32_16x16x32_bf16 v[22:25], v[146:149], v[162:165], v[22:25]
	v_mfma_f32_16x16x32_bf16 v[14:17], v[154:157], v[162:165], v[14:17]
	v_mfma_f32_16x16x32_bf16 v[6:9], v[146:149], v[170:173], v[6:9]
	v_mfma_f32_16x16x32_bf16 v[2:5], v[154:157], v[170:173], v[2:5]
	v_mfma_f32_16x16x32_bf16 v[118:121], v[146:149], v[200:203], v[118:121]
	v_mfma_f32_16x16x32_bf16 v[114:117], v[154:157], v[200:203], v[114:117]
	v_mfma_f32_16x16x32_bf16 v[102:105], v[146:149], v[208:211], v[102:105]
	v_mfma_f32_16x16x32_bf16 v[98:101], v[154:157], v[208:211], v[98:101]
	v_mfma_f32_16x16x32_bf16 v[22:25], v[150:153], v[166:169], v[22:25]
	v_mfma_f32_16x16x32_bf16 v[14:17], v[158:161], v[166:169], v[14:17]
	v_mfma_f32_16x16x32_bf16 v[6:9], v[150:153], v[174:177], v[6:9]
	v_mfma_f32_16x16x32_bf16 v[2:5], v[158:161], v[174:177], v[2:5]
	v_mfma_f32_16x16x32_bf16 v[118:121], v[150:153], v[204:207], v[118:121]
	v_mfma_f32_16x16x32_bf16 v[114:117], v[158:161], v[204:207], v[114:117]
	v_mfma_f32_16x16x32_bf16 v[102:105], v[150:153], v[212:215], v[102:105]
	v_mfma_f32_16x16x32_bf16 v[98:101], v[158:161], v[212:215], v[98:101]
	s_barrier
	s_mov_b32 m0, s7
	v_lshl_add_u64 v[216:217], v[216:217], 0, s[58:59]
	ds_read_b128 v[162:165], v246 offset:49152
	ds_read_b128 v[166:169], v246 offset:50176
	ds_read_b128 v[170:173], v246 offset:51200
	ds_read_b128 v[174:177], v246 offset:52224
	ds_read_b128 v[200:203], v246 offset:53248
	ds_read_b128 v[204:207], v246 offset:54272
	ds_read_b128 v[208:211], v246 offset:55296
	ds_read_b128 v[212:215], v246 offset:56320
	global_load_lds_dwordx4 v[216:217], off
	v_lshl_add_u64 v[216:217], v[218:219], 0, s[58:59]
	s_mov_b32 m0, s86
	s_nop 0
	global_load_lds_dwordx4 v[216:217], off
	v_lshl_add_u64 v[216:217], v[220:221], 0, s[58:59]
	s_mov_b32 m0, s95
	s_nop 0
	global_load_lds_dwordx4 v[216:217], off
	v_lshl_add_u64 v[216:217], v[222:223], 0, s[58:59]
	s_mov_b32 m0, s74
	s_nop 0
	global_load_lds_dwordx4 v[216:217], off
	v_lshl_add_u64 v[216:217], v[224:225], 0, s[58:59]
	s_mov_b32 m0, s87
	s_nop 0
	global_load_lds_dwordx4 v[216:217], off
	v_lshl_add_u64 v[216:217], v[226:227], 0, s[58:59]
	s_mov_b32 m0, s75
	s_nop 0
	global_load_lds_dwordx4 v[216:217], off
	s_waitcnt vmcnt(8)
	s_waitcnt lgkmcnt(0)
	s_barrier
	s_waitcnt lgkmcnt(0)
	v_mfma_f32_16x16x32_bf16 v[94:97], v[130:133], v[162:165], v[94:97]
	v_mfma_f32_16x16x32_bf16 v[90:93], v[138:141], v[162:165], v[90:93]
	v_mfma_f32_16x16x32_bf16 v[78:81], v[130:133], v[170:173], v[78:81]
	v_mfma_f32_16x16x32_bf16 v[74:77], v[138:141], v[170:173], v[74:77]
	v_mfma_f32_16x16x32_bf16 v[62:65], v[130:133], v[200:203], v[62:65]
	v_mfma_f32_16x16x32_bf16 v[58:61], v[138:141], v[200:203], v[58:61]
	v_mfma_f32_16x16x32_bf16 v[46:49], v[130:133], v[208:211], v[46:49]
	v_mfma_f32_16x16x32_bf16 v[42:45], v[138:141], v[208:211], v[42:45]
	v_mfma_f32_16x16x32_bf16 v[94:97], v[134:137], v[166:169], v[94:97]
	v_mfma_f32_16x16x32_bf16 v[90:93], v[142:145], v[166:169], v[90:93]
	v_mfma_f32_16x16x32_bf16 v[78:81], v[134:137], v[174:177], v[78:81]
	v_mfma_f32_16x16x32_bf16 v[74:77], v[142:145], v[174:177], v[74:77]
	v_mfma_f32_16x16x32_bf16 v[62:65], v[134:137], v[204:207], v[62:65]
	v_mfma_f32_16x16x32_bf16 v[58:61], v[142:145], v[204:207], v[58:61]
	v_mfma_f32_16x16x32_bf16 v[46:49], v[134:137], v[212:215], v[46:49]
	v_mfma_f32_16x16x32_bf16 v[42:45], v[142:145], v[212:215], v[42:45]
	v_mfma_f32_16x16x32_bf16 v[86:89], v[146:149], v[162:165], v[86:89]
	v_mfma_f32_16x16x32_bf16 v[82:85], v[154:157], v[162:165], v[82:85]
	v_mfma_f32_16x16x32_bf16 v[70:73], v[146:149], v[170:173], v[70:73]
	v_mfma_f32_16x16x32_bf16 v[66:69], v[154:157], v[170:173], v[66:69]
	v_mfma_f32_16x16x32_bf16 v[54:57], v[146:149], v[200:203], v[54:57]
	v_mfma_f32_16x16x32_bf16 v[50:53], v[154:157], v[200:203], v[50:53]
	v_mfma_f32_16x16x32_bf16 v[38:41], v[146:149], v[208:211], v[38:41]
	v_mfma_f32_16x16x32_bf16 v[34:37], v[154:157], v[208:211], v[34:37]
	v_mfma_f32_16x16x32_bf16 v[86:89], v[150:153], v[166:169], v[86:89]
	v_mfma_f32_16x16x32_bf16 v[82:85], v[158:161], v[166:169], v[82:85]
	v_mfma_f32_16x16x32_bf16 v[70:73], v[150:153], v[174:177], v[70:73]
	v_mfma_f32_16x16x32_bf16 v[66:69], v[158:161], v[174:177], v[66:69]
	v_mfma_f32_16x16x32_bf16 v[54:57], v[150:153], v[204:207], v[54:57]
	v_mfma_f32_16x16x32_bf16 v[50:53], v[158:161], v[204:207], v[50:53]
	v_mfma_f32_16x16x32_bf16 v[38:41], v[150:153], v[212:215], v[38:41]
	v_mfma_f32_16x16x32_bf16 v[34:37], v[158:161], v[212:215], v[34:37]
	s_barrier
	s_add_u32 s0, s0, 0x100
	s_addc_u32 s1, s1, 0
	s_add_u32 s12, s12, 0x100
	s_addc_u32 s13, s13, 0
	s_cmp_ge_u32 s14, s33
	s_mov_b32 s10, s14
	s_cbranch_scc0 .LBB0_66
	v_readlane_b32 s0, v254, 13
	v_readlane_b32 s1, v254, 14
	s_and_b64 vcc, exec, s[0:1]
	s_cbranch_vccz .LBB0_69
	s_barrier
